# baseline (speedup 1.0000x reference)
; __device__ __forceinline__ void finishSM(f32x16& p0, f32x16& p1, float alpha, float& l_reg, bf16x8& pa0, bf16x8& pa1, bf16x8& pa2, bf16x8& pa3) {
;     ...
;   for (int r = 0; r < 16; ++r) p1[r] = __builtin_amdgcn_exp2f(p1[r]);
;   float ps = 0;
; #pragma unroll
;   for (int r = 0; r < 16; ++r) ps += p0[r];
; #pragma unroll
;   for (int r = 0; r < 16; ++r) ps += p1[r];
;   { auto rr = __builtin_amdgcn_permlane32_swap(__float_as_uint(ps), __float_as_uint(ps), false, false);
;     ps = __uint_as_float(rr[0]) + __uint_as_float(rr[1]); }
;   l_reg = l_reg * alpha + ps;
;     ...
;   PK4(p0, 0, pa0); PK4(p0, 8, pa1); PK4(p1, 0, pa2); PK4(p1, 8, pa3);
; __device__ __forceinline__ void qkt(f32x16& p0, f32x16& p1, const char* Ks, const char* Krs, const bf16x8* qr, const char* Qrs, int r32, int hi) {
;     ...
;   for (int d0 = 0; d0 < 8; ++d0) { const int cb = (d0 * 16 + hi * 8) * 2;
;     const bf16x8 b0 = *reinterpret_cast<const bf16x8*>(Ks + KSWZ(r32, cb));
;     const bf16x8 b1 = *reinterpret_cast<const bf16x8*>(Ks + KSWZ(32 + r32, cb));
;     p0 = __builtin_amdgcn_mfma_f32_32x32x16_bf16(b0, qr[d0], p0, 0, 0, 0);
;     p1 = __builtin_amdgcn_mfma_f32_32x32x16_bf16(b1, qr[d0], p1, 0, 0, 0); }
; #pragma unroll
;   for (int d0 = 0; d0 < 4; ++d0) { const int slot = d0 * 2 + hi;
;     const bf16x8 b0 = *reinterpret_cast<const bf16x8*>(Krs + RSWZ(r32, slot));
;     const bf16x8 b1 = *reinterpret_cast<const bf16x8*>(Krs + RSWZ(32 + r32, slot));
;     const bf16x8 qf = *reinterpret_cast<const bf16x8*>(Qrs + RSWZ(r32, slot));
;     p0 = __builtin_amdgcn_mfma_f32_32x32x16_bf16(b0, qf, p0, 0, 0, 0);
;     p1 = __builtin_amdgcn_mfma_f32_32x32x16_bf16(b1, qf, p1, 0, 0, 0); }
.LBB0_353:
	s_add_u32 s46, s70, 0x20000
	s_addc_u32 s47, s71, 0
	ds_read_b128 v[64:67], v169 offset:49152
	ds_read_b128 v[68:71], v169 offset:57344
	ds_read_b128 v[196:199], v170 offset:49152
	ds_read_b128 v[204:207], v170 offset:57344
	ds_read_b128 v[238:241], v171 offset:49152
	ds_read_b128 v[242:245], v171 offset:57344
	v_or_b32_e32 v164, 0x12000, v181
	v_or_b32_e32 v165, 0x13000, v181
	v_add_u32_e32 v168, v155, v181
	v_or_b32_e32 v167, 0x12000, v184
	v_add_u32_e32 v187, v155, v184
	v_exp_f32_e32 v158, v134
	v_add_f32_e32 v134, 0, v213
	s_add_u32 m0, s98, 0x8000
	s_waitcnt lgkmcnt(5)
	v_mfma_f32_32x32x16_bf16 v[80:95], v[64:67], v[124:127], 0
	global_load_lds_dwordx4 v130, s[70:71]
	v_add_f32_e32 v134, v217, v134
	v_add_f32_e32 v134, v218, v134
	v_add_f32_e32 v134, v220, v134
	v_add_f32_e32 v134, v221, v134
	v_add_f32_e32 v134, v223, v134
	v_add_f32_e32 v134, v222, v134
	v_add_f32_e32 v134, v224, v134
	s_waitcnt lgkmcnt(4)
	v_mfma_f32_32x32x16_bf16 v[64:79], v[68:71], v[124:127], 0
	v_add_f32_e32 v134, v209, v134
	v_add_f32_e32 v134, v210, v134
	v_add_f32_e32 v134, v211, v134
	v_add_f32_e32 v134, v214, v134
	v_exp_f32_e32 v146, v146
	v_add_f32_e32 v134, v212, v134
	v_exp_f32_e32 v147, v147
	s_waitcnt lgkmcnt(3)
	v_mfma_f32_32x32x16_bf16 v[80:95], v[196:199], v[120:123], v[80:95]
	v_add_f32_e32 v134, v215, v134
	v_exp_f32_e32 v144, v144
	v_add_f32_e32 v134, v216, v134
	v_exp_f32_e32 v145, v145
	v_add_f32_e32 v134, v219, v134
	v_or_b32_e32 v203, 0x13000, v184
	v_exp_f32_e32 v150, v140
	s_waitcnt lgkmcnt(2)
	v_mfma_f32_32x32x16_bf16 v[64:79], v[204:207], v[120:123], v[64:79]
	ds_read_b128 v[196:199], v172 offset:49152
	ds_read_b128 v[204:207], v172 offset:57344
	v_add_f32_e32 v134, v146, v134
	v_exp_f32_e32 v151, v141
	v_add_f32_e32 v134, v147, v134
	v_exp_f32_e32 v156, v136
	v_add_f32_e32 v134, v144, v134
	v_exp_f32_e32 v157, v137
	s_add_u32 m0, s98, 0xa000
	s_waitcnt lgkmcnt(3)
	v_mfma_f32_32x32x16_bf16 v[80:95], v[238:241], v[116:119], v[80:95]
	global_load_lds_dwordx4 v130, s[46:47]
	v_add_f32_e32 v134, v145, v134
	v_add_f32_e32 v134, v150, v134
	v_exp_f32_e32 v159, v135
	v_add_f32_e32 v134, v151, v134
	v_exp_f32_e32 v148, v148
	v_add_f32_e32 v134, v156, v134
	v_exp_f32_e32 v149, v149
	s_waitcnt lgkmcnt(2)
	v_mfma_f32_32x32x16_bf16 v[64:79], v[242:245], v[116:119], v[64:79]
	ds_read_b128 v[238:241], v173 offset:49152
	ds_read_b128 v[242:245], v173 offset:57344
	v_add_f32_e32 v134, v157, v134
	v_add_f32_e32 v134, v158, v134
	v_exp_f32_e32 v208, v143
	v_add_f32_e32 v134, v159, v134
	v_exp_f32_e32 v225, v138
	v_add_f32_e32 v134, v148, v134
	s_waitcnt lgkmcnt(3)
	v_mfma_f32_32x32x16_bf16 v[80:95], v[196:199], v[112:115], v[80:95]
	v_add_f32_e32 v134, v149, v134
	v_cvt_pk_bf16_f32 v136, v221, v223
	v_cvt_pk_bf16_f32 v135, v218, v220
	v_cvt_pk_bf16_f32 v137, v222, v224
	v_cvt_pk_bf16_f32 v138, v209, v210
	v_cvt_pk_bf16_f32 v140, v212, v215
	v_cvt_pk_bf16_f32 v141, v216, v219
	s_waitcnt lgkmcnt(2)
	v_mfma_f32_32x32x16_bf16 v[64:79], v[204:207], v[112:115], v[64:79]
	ds_read_b128 v[196:199], v174 offset:49152
	ds_read_b128 v[204:207], v174 offset:57344
	v_cvt_pk_bf16_f32 v143, v144, v145
	v_cvt_pk_bf16_f32 v144, v150, v151
	v_cvt_pk_bf16_f32 v145, v156, v157
	v_permlane32_swap_b32_e32 v135, v137
	v_permlane32_swap_b32_e32 v138, v140
	s_add_u32 m0, s98, 0x10000
	s_waitcnt lgkmcnt(3)
	v_mfma_f32_32x32x16_bf16 v[80:95], v[238:241], v[108:111], v[80:95]
	global_load_lds_dwordx4 v132, s[72:73]
	v_permlane32_swap_b32_e32 v143, v145
	s_waitcnt lgkmcnt(2)
	v_mfma_f32_32x32x16_bf16 v[64:79], v[242:245], v[108:111], v[64:79]
	ds_read_b128 v[238:241], v175 offset:49152
	ds_read_b128 v[242:245], v175 offset:57344
	s_waitcnt lgkmcnt(3)
	v_mfma_f32_32x32x16_bf16 v[80:95], v[196:199], v[104:107], v[80:95]
	s_waitcnt lgkmcnt(2)
	v_mfma_f32_32x32x16_bf16 v[64:79], v[204:207], v[104:107], v[64:79]
	ds_read_b128 v[196:199], v176 offset:49152
	ds_read_b128 v[204:207], v176 offset:57344
	s_add_u32 m0, s98, 0x4000
	s_waitcnt lgkmcnt(3)
	v_mfma_f32_32x32x16_bf16 v[80:95], v[238:241], v[100:103], v[80:95]
	global_load_lds_dwordx4 v131, s[70:71]
	s_waitcnt lgkmcnt(2)
	v_mfma_f32_32x32x16_bf16 v[64:79], v[242:245], v[100:103], v[64:79]
	ds_read_b128 v[238:241], v193
	ds_read_b128 v[242:245], v194
	ds_read_b128 v[246:249], v192
	s_waitcnt lgkmcnt(4)
	v_mfma_f32_32x32x16_bf16 v[80:95], v[196:199], v[96:99], v[80:95]
	s_waitcnt lgkmcnt(3)
	v_mfma_f32_32x32x16_bf16 v[64:79], v[204:207], v[96:99], v[64:79]
	ds_read_b128 v[196:199], v189
	ds_read_b128 v[204:207], v190
	ds_read_b128 v[226:229], v191
	s_add_u32 m0, s98, 0x6000
	s_waitcnt lgkmcnt(3)
	v_mfma_f32_32x32x16_bf16 v[80:95], v[238:241], v[246:249], v[80:95]
	global_load_lds_dwordx4 v131, s[46:47]
	s_add_u32 s70, s70, 0x40000
	s_addc_u32 s71, s71, 0
	s_add_u32 s72, s72, 0x2000
	s_addc_u32 s73, s73, 0
	s_waitcnt lgkmcnt(3)
	v_mfma_f32_32x32x16_bf16 v[64:79], v[242:245], v[246:249], v[64:79]
	ds_read_b128 v[238:241], v164
	ds_read_b128 v[242:245], v165
	ds_read_b128 v[246:249], v168
	s_waitcnt lgkmcnt(3)
	v_mfma_f32_32x32x16_bf16 v[80:95], v[196:199], v[226:229], v[80:95]
	s_waitcnt lgkmcnt(3)
	v_mfma_f32_32x32x16_bf16 v[64:79], v[204:207], v[226:229], v[64:79]
	ds_read_b128 v[196:199], v167
	ds_read_b128 v[164:167], v203
	ds_read_b128 v[234:237], v187
	s_waitcnt lgkmcnt(3)
	v_mfma_f32_32x32x16_bf16 v[80:95], v[238:241], v[246:249], v[80:95]
	v_exp_f32_e32 v207, v142
	v_cvt_pk_bf16_f32 v142, v146, v147
	v_cvt_pk_bf16_f32 v146, v158, v159
	v_cvt_pk_bf16_f32 v147, v148, v149
	v_add_f32_e32 v134, v207, v134
	s_waitcnt lgkmcnt(3)
; __device__ __forceinline__ void qkt(f32x16& p0, f32x16& p1, const char* Ks, const char* Krs, const bf16x8* qr, const char* Qrs, int r32, int hi) {
;   p0 = f32x16{}; p1 = f32x16{};
; #pragma unroll
;   for (int d0 = 0; d0 < 8; ++d0) { const int cb = (d0 * 16 + hi * 8) * 2;
;     const bf16x8 b0 = *reinterpret_cast<const bf16x8*>(Ks + KSWZ(r32, cb));
;     const bf16x8 b1 = *reinterpret_cast<const bf16x8*>(Ks + KSWZ(32 + r32, cb));
;     p0 = __builtin_amdgcn_mfma_f32_32x32x16_bf16(b0, qr[d0], p0, 0, 0, 0);
;     p1 = __builtin_amdgcn_mfma_f32_32x32x16_bf16(b1, qr[d0], p1, 0, 0, 0); }
; #pragma unroll
;   for (int d0 = 0; d0 < 4; ++d0) { const int slot = d0 * 2 + hi;
;     const bf16x8 b0 = *reinterpret_cast<const bf16x8*>(Krs + RSWZ(r32, slot));
;     const bf16x8 b1 = *reinterpret_cast<const bf16x8*>(Krs + RSWZ(32 + r32, slot));
;     const bf16x8 qf = *reinterpret_cast<const bf16x8*>(Qrs + RSWZ(r32, slot));
;     p0 = __builtin_amdgcn_mfma_f32_32x32x16_bf16(b0, qf, p0, 0, 0, 0);
;     p1 = __builtin_amdgcn_mfma_f32_32x32x16_bf16(b1, qf, p1, 0, 0, 0); }
; }
; __device__ __forceinline__ int v_st(int k, int c) { const int kk = (k & ~0xC) | ((k & 4) << 1) | ((k & 8) >> 1); return ((kk >> 3) * 4 + (c >> 5)) * 512 + ((kk & 7) * 32 + (c & 31)) * 2; }
; __device__ __forceinline__ int v_rd_base(int lane) { return ((lane & 3) << 3) | (((lane >> 2) & 3) << 6) | (((lane >> 4) & 1) << 5) | (((lane >> 5) & 1) << 8); }
; template <int OFF> __device__ __forceinline__ s16x4 tr_read(int vb) {
;   s16x4 r; asm volatile("ds_read_b64_tr_b16 %0, %1 offset:%2" : "=&v"(r) : "v"(vb), "i"(OFF) : "memory"); return r;
; }
; template <int D0> __device__ __forceinline__ void pv_one(f32x16& od, int vb, bf16x8 pa0, bf16x8 pa1, bf16x8 pa2, bf16x8 pa3) {
;   const s16x4 l0 = tr_read<v_rd_off(D0, 0, 0)>(vb), h0 = tr_read<v_rd_off(D0, 0, 1)>(vb), l1 = tr_read<v_rd_off(D0, 1, 0)>(vb), h1 = tr_read<v_rd_off(D0, 1, 1)>(vb);
;   const s16x4 l2 = tr_read<v_rd_off(D0, 2, 0)>(vb), h2 = tr_read<v_rd_off(D0, 2, 1)>(vb), l3 = tr_read<v_rd_off(D0, 3, 0)>(vb), h3 = tr_read<v_rd_off(D0, 3, 1)>(vb);
;   asm volatile("s_waitcnt lgkmcnt(0)" ::: "memory"); SBAR();
;     ...
;   od = __builtin_amdgcn_mfma_f32_32x32x16_bf16(pa0, PK(l0, h0), od, 0, 0, 0);
;   od = __builtin_amdgcn_mfma_f32_32x32x16_bf16(pa1, PK(l1, h1), od, 0, 0, 0);
;   od = __builtin_amdgcn_mfma_f32_32x32x16_bf16(pa2, PK(l2, h2), od, 0, 0, 0);
	v_mfma_f32_32x32x16_bf16 v[64:79], v[242:245], v[246:249], v[64:79]
	ds_read_b64_tr_b16 v[230:231], v163 offset:0
	ds_read_b64_tr_b16 v[232:233], v163 offset:0x800
	ds_read_b64_tr_b16 v[238:239], v163 offset:0x2000
	ds_read_b64_tr_b16 v[240:241], v163 offset:0x2800
	ds_read_b64_tr_b16 v[242:243], v163 offset:0x3000
	ds_read_b64_tr_b16 v[244:245], v163 offset:0x3800
	v_add_f32_e32 v134, v208, v134
	v_add_f32_e32 v134, v225, v134
	v_cvt_pk_bf16_f32 v148, v207, v208
	v_permlane32_swap_b32_e32 v142, v144
	s_waitcnt lgkmcnt(6)
	v_mfma_f32_32x32x16_bf16 v[80:95], v[196:199], v[234:237], v[80:95]
	v_exp_f32_e32 v226, v139
	v_cvt_pk_bf16_f32 v139, v211, v214
	s_nop 1
	v_permlane32_swap_b32_e32 v139, v141
	v_add_f32_e32 v205, v226, v134
	v_mov_b32_e32 v206, v205
	v_cvt_pk_bf16_f32 v134, v213, v217
	s_waitcnt lgkmcnt(6)
	v_mfma_f32_32x32x16_bf16 v[64:79], v[164:167], v[234:237], v[64:79]
	v_permlane32_swap_b32_e32 v205, v206
	v_permlane32_swap_b32_e32 v134, v136
	v_cvt_pk_bf16_f32 v149, v225, v226
	v_permlane32_swap_b32_e32 v146, v148
	s_nop 0
	v_permlane32_swap_b32_e32 v147, v149
	ds_read_b64_tr_b16 v[234:235], v163 offset:0x1000
	ds_read_b64_tr_b16 v[236:237], v163 offset:0x1800
	s_waitcnt lgkmcnt(2)
	s_nop 0
	v_mfma_f32_32x32x16_bf16 v[48:63], v[134:137], v[230:233], v[48:63]
	ds_read_b64_tr_b16 v[230:231], v163 offset:0x200
	ds_read_b64_tr_b16 v[232:233], v163 offset:0xa00
	v_max_f32_e32 v164, v81, v81
	v_max_f32_e32 v165, v80, v80
	v_max_f32_e32 v164, v165, v164
	v_max3_f32 v164, v164, v82, v83
	v_max3_f32 v164, v164, v84, v85
	s_waitcnt lgkmcnt(2)
	v_mfma_f32_32x32x16_bf16 v[48:63], v[138:141], v[234:237], v[48:63]
	ds_read_b64_tr_b16 v[234:235], v163 offset:0x1200
	ds_read_b64_tr_b16 v[236:237], v163 offset:0x1a00
	v_max3_f32 v164, v164, v86, v87
	v_max3_f32 v164, v164, v88, v89
	v_max3_f32 v164, v164, v90, v91
	v_max3_f32 v164, v164, v92, v93
	v_max3_f32 v164, v164, v94, v95
	v_mfma_f32_32x32x16_bf16 v[48:63], v[142:145], v[238:241], v[48:63]
	ds_read_b64_tr_b16 v[238:239], v163 offset:0x2200
	ds_read_b64_tr_b16 v[240:241], v163 offset:0x2a00
	ds_read_b64_tr_b16 v[246:247], v163 offset:0x3200
	ds_read_b64_tr_b16 v[248:249], v163 offset:0x3a00
	v_max3_f32 v164, v164, v64, v65
	v_max3_f32 v164, v164, v66, v67
	v_max3_f32 v164, v164, v68, v69
	v_max3_f32 v164, v164, v70, v71
	v_max3_f32 v164, v164, v72, v73
	s_waitcnt lgkmcnt(0)
	v_mfma_f32_32x32x16_bf16 v[48:63], v[146:149], v[242:245], v[48:63]
	v_max3_f32 v164, v164, v74, v75
	v_max3_f32 v164, v164, v76, v77
	v_max3_f32 v164, v164, v78, v79
	v_mfma_f32_32x32x16_bf16 v[32:47], v[134:137], v[230:233], v[32:47]
	ds_read_b64_tr_b16 v[230:231], v163 offset:0x400
	ds_read_b64_tr_b16 v[232:233], v163 offset:0xc00
	v_mov_b32_e32 v165, v164
	s_nop 1
	v_permlane32_swap_b32_e32 v164, v165
	v_max_f32_e32 v165, v165, v165
	v_max_f32_e32 v164, v164, v164
	v_max_f32_e32 v164, v164, v165
	v_mfma_f32_32x32x16_bf16 v[32:47], v[138:141], v[234:237], v[32:47]
	ds_read_b64_tr_b16 v[234:235], v163 offset:0x1400
	ds_read_b64_tr_b16 v[236:237], v163 offset:0x1c00
	v_max_f32_e32 v166, v195, v195
	v_sub_f32_e32 v165, v164, v195
	v_max_f32_e32 v164, v166, v164
	v_sub_f32_e32 v166, v195, v164
	v_mul_f32_e32 v166, 0x3dd53b94, v166
	v_mfma_f32_32x32x16_bf16 v[32:47], v[142:145], v[238:241], v[32:47]
	ds_read_b64_tr_b16 v[238:239], v163 offset:0x2400
	ds_read_b64_tr_b16 v[240:241], v163 offset:0x2c00
	ds_read_b64_tr_b16 v[242:243], v163 offset:0x3400
	ds_read_b64_tr_b16 v[244:245], v163 offset:0x3c00
	v_exp_f32_e32 v166, v166
	v_cmp_ge_f32_e32 vcc, s69, v165
	s_cmp_eq_u64 vcc, exec
	s_cselect_b64 s[8:9], -1, 0
	v_cndmask_b32_e64 v208, v166, 1.0, s[8:9]
	v_cndmask_b32_e64 v167, v164, v195, s[8:9]
	v_mul_f32_e32 v207, 0xbdd53b94, v167
	s_waitcnt lgkmcnt(0)
	v_mfma_f32_32x32x16_bf16 v[32:47], v[146:149], v[246:249], v[32:47]
	v_fmamk_f32 v80, v80, 0x3dd53b94, v207
	v_fmamk_f32 v81, v81, 0x3dd53b94, v207
	v_fmamk_f32 v82, v82, 0x3dd53b94, v207
	v_fmamk_f32 v83, v83, 0x3dd53b94, v207
	v_fmamk_f32 v84, v84, 0x3dd53b94, v207
	v_fmamk_f32 v85, v85, 0x3dd53b94, v207
	v_mfma_f32_32x32x16_bf16 v[16:31], v[134:137], v[230:233], v[16:31]
	ds_read_b64_tr_b16 v[230:231], v163 offset:0x600
	ds_read_b64_tr_b16 v[232:233], v163 offset:0xe00
	v_fmamk_f32 v86, v86, 0x3dd53b94, v207
	v_fmamk_f32 v87, v87, 0x3dd53b94, v207
	v_fmamk_f32 v88, v88, 0x3dd53b94, v207
	v_fmamk_f32 v89, v89, 0x3dd53b94, v207
	v_fmamk_f32 v90, v90, 0x3dd53b94, v207
	v_fmamk_f32 v91, v91, 0x3dd53b94, v207
	v_mfma_f32_32x32x16_bf16 v[16:31], v[138:141], v[234:237], v[16:31]
	ds_read_b64_tr_b16 v[234:235], v163 offset:0x1600
	ds_read_b64_tr_b16 v[236:237], v163 offset:0x1e00
	v_fmamk_f32 v92, v92, 0x3dd53b94, v207
	v_fmamk_f32 v93, v93, 0x3dd53b94, v207
	v_fmamk_f32 v94, v94, 0x3dd53b94, v207
	v_fmamk_f32 v95, v95, 0x3dd53b94, v207
	v_fmamk_f32 v217, v64, 0x3dd53b94, v207
	v_fmamk_f32 v218, v65, 0x3dd53b94, v207
	v_mfma_f32_32x32x16_bf16 v[16:31], v[142:145], v[238:241], v[16:31]
	ds_read_b64_tr_b16 v[238:239], v163 offset:0x2600
	ds_read_b64_tr_b16 v[240:241], v163 offset:0x2e00
	ds_read_b64_tr_b16 v[246:247], v163 offset:0x3600
	ds_read_b64_tr_b16 v[248:249], v163 offset:0x3e00
	v_fmamk_f32 v219, v66, 0x3dd53b94, v207
	v_fmamk_f32 v220, v67, 0x3dd53b94, v207
	v_fmamk_f32 v221, v68, 0x3dd53b94, v207
	v_fmamk_f32 v210, v69, 0x3dd53b94, v207
	v_fmamk_f32 v211, v70, 0x3dd53b94, v207
	v_fmamk_f32 v212, v71, 0x3dd53b94, v207
	s_waitcnt lgkmcnt(0)
	v_mfma_f32_32x32x16_bf16 v[16:31], v[146:149], v[242:245], v[16:31]
	v_fmamk_f32 v213, v72, 0x3dd53b94, v207
	v_fmamk_f32 v214, v73, 0x3dd53b94, v207
	v_fmamk_f32 v215, v74, 0x3dd53b94, v207
	v_fmamk_f32 v216, v75, 0x3dd53b94, v207
	v_exp_f32_e32 v195, v85
	v_mfma_f32_32x32x16_bf16 v[0:15], v[134:137], v[230:233], v[0:15]
	v_mov_b32_e32 v134, v167
	v_fmamk_f32 v209, v76, 0x3dd53b94, v207
	v_fmamk_f32 v222, v77, 0x3dd53b94, v207
	v_fmamk_f32 v223, v78, 0x3dd53b94, v207
	v_fmac_f32_e32 v207, 0x3dd53b94, v79
	v_exp_f32_e32 v135, v88
	v_mfma_f32_32x32x16_bf16 v[0:15], v[138:141], v[234:237], v[0:15]
	v_exp_f32_e32 v136, v92
	v_exp_f32_e32 v137, v89
	v_exp_f32_e32 v138, v90
	v_exp_f32_e32 v139, v93
	v_mfma_f32_32x32x16_bf16 v[0:15], v[142:145], v[238:241], v[0:15]
	v_exp_f32_e32 v140, v94
	v_exp_f32_e32 v141, v91
	v_exp_f32_e32 v142, v95
	v_exp_f32_e32 v143, v80
	v_exp_f32_e32 v144, v81
	v_mfma_f32_32x32x16_bf16 v[0:15], v[146:149], v[246:249], v[0:15]
	v_exp_f32_e32 v145, v82
	v_exp_f32_e32 v146, v86
	v_exp_f32_e32 v147, v83
	v_exp_f32_e32 v148, v84
	v_exp_f32_e32 v149, v87
	v_cmp_gt_f32_e32 vcc, 1.0, v208
	s_cbranch_vccz .LBB0_357
; __device__ __forceinline__ void finishSM(f32x16& p0, f32x16& p1, float alpha, float& l_reg, bf16x8& pa0, bf16x8& pa1, bf16x8& pa2, bf16x8& pa3) {
; #pragma unroll
;   for (int r = 0; r < 16; ++r) p1[r] = __builtin_amdgcn_exp2f(p1[r]);
;   float ps = 0;
; #pragma unroll
;   for (int r = 0; r < 16; ++r) ps += p0[r];
; #pragma unroll
;   for (int r = 0; r < 16; ++r) ps += p1[r];
;   { auto rr = __builtin_amdgcn_permlane32_swap(__float_as_uint(ps), __float_as_uint(ps), false, false);
;     ps = __uint_as_float(rr[0]) + __uint_as_float(rr[1]); }
;   l_reg = l_reg * alpha + ps;
;     ...
;   PK4(p0, 0, pa0); PK4(p0, 8, pa1); PK4(p1, 0, pa2); PK4(p1, 8, pa3);
;     ...
; }
; __device__ __forceinline__ void qkt(f32x16& p0, f32x16& p1, const char* Ks, const char* Krs, const bf16x8* qr, const char* Qrs, int r32, int hi) {
;   p0 = f32x16{}; p1 = f32x16{};
; #pragma unroll
;   for (int d0 = 0; d0 < 8; ++d0) { const int cb = (d0 * 16 + hi * 8) * 2;
;     const bf16x8 b0 = *reinterpret_cast<const bf16x8*>(Ks + KSWZ(r32, cb));
;     const bf16x8 b1 = *reinterpret_cast<const bf16x8*>(Ks + KSWZ(32 + r32, cb));
;     p0 = __builtin_amdgcn_mfma_f32_32x32x16_bf16(b0, qr[d0], p0, 0, 0, 0);
;     p1 = __builtin_amdgcn_mfma_f32_32x32x16_bf16(b1, qr[d0], p1, 0, 0, 0); }
; #pragma unroll
;   for (int d0 = 0; d0 < 4; ++d0) { const int slot = d0 * 2 + hi;
;     const bf16x8 b0 = *reinterpret_cast<const bf16x8*>(Krs + RSWZ(r32, slot));
;     const bf16x8 b1 = *reinterpret_cast<const bf16x8*>(Krs + RSWZ(32 + r32, slot));
;     const bf16x8 qf = *reinterpret_cast<const bf16x8*>(Qrs + RSWZ(r32, slot));
;     p0 = __builtin_amdgcn_mfma_f32_32x32x16_bf16(b0, qf, p0, 0, 0, 0);
;     p1 = __builtin_amdgcn_mfma_f32_32x32x16_bf16(b1, qf, p1, 0, 0, 0); }
; }
	s_and_saveexec_b64 s[10:11], s[6:7]
	ds_write_b32 v160, v208 offset:128
	s_or_b64 exec, exec, s[10:11]
	s_waitcnt lgkmcnt(0)
	v_add_u32_e32 v246, v253, v128
	ds_read_b128 v[230:233], v246 offset:224
	ds_read_b128 v[234:237], v246 offset:192
	ds_read_b128 v[238:241], v246 offset:160
	ds_read_b128 v[242:245], v246 offset:128
	s_waitcnt lgkmcnt(3)
	v_pk_mul_f32 v[60:61], v[60:61], v[230:231]
	s_waitcnt lgkmcnt(2)
	v_pk_mul_f32 v[56:57], v[56:57], v[234:235]
	s_waitcnt lgkmcnt(1)
	v_pk_mul_f32 v[52:53], v[52:53], v[238:239]
	v_pk_mul_f32 v[62:63], v[62:63], v[232:233]
	v_pk_mul_f32 v[58:59], v[58:59], v[236:237]
	v_pk_mul_f32 v[54:55], v[54:55], v[240:241]
	s_waitcnt lgkmcnt(0)
	v_pk_mul_f32 v[50:51], v[50:51], v[244:245]
	v_pk_mul_f32 v[48:49], v[48:49], v[242:243]
	v_pk_mul_f32 v[44:45], v[44:45], v[230:231]
	v_pk_mul_f32 v[40:41], v[40:41], v[234:235]
	v_pk_mul_f32 v[36:37], v[36:37], v[238:239]
	v_pk_mul_f32 v[46:47], v[46:47], v[232:233]
	v_pk_mul_f32 v[42:43], v[42:43], v[236:237]
	v_pk_mul_f32 v[38:39], v[38:39], v[240:241]
	v_pk_mul_f32 v[34:35], v[34:35], v[244:245]
	v_pk_mul_f32 v[32:33], v[32:33], v[242:243]
	v_pk_mul_f32 v[28:29], v[28:29], v[230:231]
	v_pk_mul_f32 v[24:25], v[24:25], v[234:235]
	v_pk_mul_f32 v[20:21], v[20:21], v[238:239]
	v_pk_mul_f32 v[30:31], v[30:31], v[232:233]
	v_pk_mul_f32 v[26:27], v[26:27], v[236:237]
	v_pk_mul_f32 v[22:23], v[22:23], v[240:241]
	v_pk_mul_f32 v[18:19], v[18:19], v[244:245]
	v_pk_mul_f32 v[16:17], v[16:17], v[242:243]
	v_pk_mul_f32 v[12:13], v[12:13], v[230:231]
	v_pk_mul_f32 v[8:9], v[8:9], v[234:235]
	v_pk_mul_f32 v[4:5], v[4:5], v[238:239]
	v_pk_mul_f32 v[14:15], v[14:15], v[232:233]
	v_pk_mul_f32 v[10:11], v[10:11], v[236:237]
	v_pk_mul_f32 v[6:7], v[6:7], v[240:241]
	v_pk_mul_f32 v[2:3], v[2:3], v[244:245]
	v_pk_mul_f32 v[0:1], v[0:1], v[242:243]
.LBB0_357:
	s_waitcnt vmcnt(0)
	s_waitcnt lgkmcnt(0)
	s_barrier
	s_add_u32 s46, s70, 0x20000
	s_addc_u32 s47, s71, 0
	ds_read_b128 v[64:67], v169 offset:32768
	ds_read_b128 v[68:71], v169 offset:40960
	ds_read_b128 v[224:227], v170 offset:32768
	ds_read_b128 v[228:231], v170 offset:40960
	ds_read_b128 v[240:243], v171 offset:32768
	ds_read_b128 v[244:247], v171 offset:40960
	v_exp_f32_e32 v159, v210
	v_add_f32_e32 v210, 0, v143
	s_add_u32 m0, s98, 0xc000
	s_waitcnt lgkmcnt(5)
	v_mfma_f32_32x32x16_bf16 v[80:95], v[64:67], v[124:127], 0
	global_load_lds_dwordx4 v130, s[70:71]
	v_add_f32_e32 v210, v144, v210
	v_add_f32_e32 v210, v145, v210
	v_add_f32_e32 v210, v147, v210
	v_add_f32_e32 v210, v148, v210
	v_add_f32_e32 v210, v195, v210
	v_add_f32_e32 v210, v146, v210
	v_add_f32_e32 v210, v149, v210
	s_waitcnt lgkmcnt(4)
	v_mfma_f32_32x32x16_bf16 v[64:79], v[68:71], v[124:127], 0
	v_add_f32_e32 v210, v135, v210
	v_add_f32_e32 v210, v137, v210
	v_add_f32_e32 v210, v138, v210
	v_add_f32_e32 v210, v141, v210
	v_exp_f32_e32 v150, v217
	v_add_f32_e32 v210, v136, v210
	v_exp_f32_e32 v151, v218
	s_waitcnt lgkmcnt(3)
	v_mfma_f32_32x32x16_bf16 v[80:95], v[224:227], v[120:123], v[80:95]
	v_add_f32_e32 v210, v139, v210
	v_exp_f32_e32 v156, v219
	v_add_f32_e32 v210, v140, v210
	v_exp_f32_e32 v157, v220
	v_add_f32_e32 v210, v142, v210
	v_exp_f32_e32 v158, v221
	v_add_f32_e32 v210, v150, v210
	s_waitcnt lgkmcnt(2)
	v_mfma_f32_32x32x16_bf16 v[64:79], v[228:231], v[120:123], v[64:79]
	ds_read_b128 v[224:227], v172 offset:32768
	ds_read_b128 v[228:231], v172 offset:40960
	v_add_f32_e32 v210, v151, v210
	v_exp_f32_e32 v217, v211
	v_add_f32_e32 v210, v156, v210
	v_exp_f32_e32 v218, v212
	v_add_f32_e32 v210, v157, v210
	v_exp_f32_e32 v219, v213
	s_add_u32 m0, s98, 0xe000
	s_waitcnt lgkmcnt(3)
	v_mfma_f32_32x32x16_bf16 v[80:95], v[240:243], v[116:119], v[80:95]
	global_load_lds_dwordx4 v130, s[46:47]
	v_add_f32_e32 v210, v158, v210
	v_exp_f32_e32 v214, v214
	v_add_f32_e32 v210, v159, v210
	v_exp_f32_e32 v215, v215
	v_add_f32_e32 v210, v217, v210
	v_exp_f32_e32 v216, v216
	v_add_f32_e32 v210, v218, v210
	s_waitcnt lgkmcnt(2)
	v_mfma_f32_32x32x16_bf16 v[64:79], v[244:247], v[116:119], v[64:79]
	ds_read_b128 v[240:243], v173 offset:32768
	ds_read_b128 v[244:247], v173 offset:40960
	v_exp_f32_e32 v209, v209
	v_add_f32_e32 v210, v219, v210
	v_exp_f32_e32 v220, v222
	v_add_f32_e32 v210, v214, v210
	v_exp_f32_e32 v221, v223
	v_add_f32_e32 v210, v215, v210
	s_waitcnt lgkmcnt(3)
	v_mfma_f32_32x32x16_bf16 v[80:95], v[224:227], v[112:115], v[80:95]
	v_exp_f32_e32 v207, v207
	v_add_f32_e32 v210, v216, v210
	v_add_f32_e32 v210, v209, v210
	v_add_f32_e32 v210, v220, v210
	v_add_f32_e32 v210, v221, v210
	v_cvt_pk_bf16_f32 v211, v145, v147
	v_cvt_pk_bf16_f32 v212, v148, v195
	s_waitcnt lgkmcnt(2)
	v_mfma_f32_32x32x16_bf16 v[64:79], v[228:231], v[112:115], v[64:79]
	ds_read_b128 v[224:227], v174 offset:32768
	ds_read_b128 v[228:231], v174 offset:40960
	v_cvt_pk_bf16_f32 v213, v146, v149
	v_cvt_pk_bf16_f32 v145, v138, v141
	v_cvt_pk_bf16_f32 v146, v136, v139
	v_cvt_pk_bf16_f32 v147, v140, v142
	v_cvt_pk_bf16_f32 v136, v150, v151
	v_cvt_pk_bf16_f32 v138, v158, v159
	s_add_u32 m0, s98, 0x12000
	s_waitcnt lgkmcnt(3)
	v_mfma_f32_32x32x16_bf16 v[80:95], v[240:243], v[108:111], v[80:95]
	global_load_lds_dwordx4 v132, s[72:73]
	v_cvt_pk_bf16_f32 v139, v217, v218
	v_cvt_pk_bf16_f32 v140, v219, v214
	v_cvt_pk_bf16_f32 v141, v215, v216
	v_cvt_pk_bf16_f32 v142, v209, v220
	v_permlane32_swap_b32_e32 v211, v213
	v_permlane32_swap_b32_e32 v145, v147
	s_waitcnt lgkmcnt(2)
	v_mfma_f32_32x32x16_bf16 v[64:79], v[244:247], v[108:111], v[64:79]
	ds_read_b128 v[240:243], v175 offset:32768
	ds_read_b128 v[244:247], v175 offset:40960
	v_permlane32_swap_b32_e32 v136, v138
	v_permlane32_swap_b32_e32 v140, v142
	s_waitcnt lgkmcnt(3)
; __device__ __forceinline__ void qkt(f32x16& p0, f32x16& p1, const char* Ks, const char* Krs, const bf16x8* qr, const char* Qrs, int r32, int hi) {
;   p0 = f32x16{}; p1 = f32x16{};
; #pragma unroll
;   for (int d0 = 0; d0 < 8; ++d0) { const int cb = (d0 * 16 + hi * 8) * 2;
;     const bf16x8 b0 = *reinterpret_cast<const bf16x8*>(Ks + KSWZ(r32, cb));
;     const bf16x8 b1 = *reinterpret_cast<const bf16x8*>(Ks + KSWZ(32 + r32, cb));
;     p0 = __builtin_amdgcn_mfma_f32_32x32x16_bf16(b0, qr[d0], p0, 0, 0, 0);
;     p1 = __builtin_amdgcn_mfma_f32_32x32x16_bf16(b1, qr[d0], p1, 0, 0, 0); }
; #pragma unroll
;   for (int d0 = 0; d0 < 4; ++d0) { const int slot = d0 * 2 + hi;
;     const bf16x8 b0 = *reinterpret_cast<const bf16x8*>(Krs + RSWZ(r32, slot));
;     const bf16x8 b1 = *reinterpret_cast<const bf16x8*>(Krs + RSWZ(32 + r32, slot));
;     const bf16x8 qf = *reinterpret_cast<const bf16x8*>(Qrs + RSWZ(r32, slot));
;     p0 = __builtin_amdgcn_mfma_f32_32x32x16_bf16(b0, qf, p0, 0, 0, 0);
;     p1 = __builtin_amdgcn_mfma_f32_32x32x16_bf16(b1, qf, p1, 0, 0, 0); }
; }
; __device__ __forceinline__ int v_st(int k, int c) { const int kk = (k & ~0xC) | ((k & 4) << 1) | ((k & 8) >> 1); return ((kk >> 3) * 4 + (c >> 5)) * 512 + ((kk & 7) * 32 + (c & 31)) * 2; }
; __device__ __forceinline__ int v_rd_base(int lane) { return ((lane & 3) << 3) | (((lane >> 2) & 3) << 6) | (((lane >> 4) & 1) << 5) | (((lane >> 5) & 1) << 8); }
; template <int OFF> __device__ __forceinline__ s16x4 tr_read(int vb) {
;   s16x4 r; asm volatile("ds_read_b64_tr_b16 %0, %1 offset:%2" : "=&v"(r) : "v"(vb), "i"(OFF) : "memory"); return r;
; }
; template <int D0> __device__ __forceinline__ void pv_one(f32x16& od, int vb, bf16x8 pa0, bf16x8 pa1, bf16x8 pa2, bf16x8 pa3) {
;   const s16x4 l0 = tr_read<v_rd_off(D0, 0, 0)>(vb), h0 = tr_read<v_rd_off(D0, 0, 1)>(vb), l1 = tr_read<v_rd_off(D0, 1, 0)>(vb), h1 = tr_read<v_rd_off(D0, 1, 1)>(vb);
;   const s16x4 l2 = tr_read<v_rd_off(D0, 2, 0)>(vb), h2 = tr_read<v_rd_off(D0, 2, 1)>(vb), l3 = tr_read<v_rd_off(D0, 3, 0)>(vb), h3 = tr_read<v_rd_off(D0, 3, 1)>(vb);
;   asm volatile("s_waitcnt lgkmcnt(0)" ::: "memory"); SBAR();
;     ...
;   od = __builtin_amdgcn_mfma_f32_32x32x16_bf16(pa0, PK(l0, h0), od, 0, 0, 0);
;   od = __builtin_amdgcn_mfma_f32_32x32x16_bf16(pa1, PK(l1, h1), od, 0, 0, 0);
;   od = __builtin_amdgcn_mfma_f32_32x32x16_bf16(pa2, PK(l2, h2), od, 0, 0, 0);
	v_mfma_f32_32x32x16_bf16 v[80:95], v[224:227], v[104:107], v[80:95]
	s_waitcnt lgkmcnt(2)
	v_mfma_f32_32x32x16_bf16 v[64:79], v[228:231], v[104:107], v[64:79]
	ds_read_b128 v[224:227], v176 offset:32768
	ds_read_b128 v[228:231], v176 offset:40960
	s_mov_b32 m0, s98
	s_waitcnt lgkmcnt(3)
	v_mfma_f32_32x32x16_bf16 v[80:95], v[240:243], v[100:103], v[80:95]
	global_load_lds_dwordx4 v131, s[70:71]
	s_waitcnt lgkmcnt(2)
	v_mfma_f32_32x32x16_bf16 v[64:79], v[244:247], v[100:103], v[64:79]
	ds_read_b128 v[240:243], v177
	ds_read_b128 v[244:247], v178
	ds_read_b128 v[248:251], v192
	s_waitcnt lgkmcnt(4)
	v_mfma_f32_32x32x16_bf16 v[80:95], v[224:227], v[96:99], v[80:95]
	s_waitcnt lgkmcnt(3)
	v_mfma_f32_32x32x16_bf16 v[64:79], v[228:231], v[96:99], v[64:79]
	ds_read_b128 v[224:227], v179
	ds_read_b128 v[228:231], v180
	ds_read_b128 v[232:235], v191
	s_add_u32 m0, s98, 0x2000
	s_waitcnt lgkmcnt(3)
	v_mfma_f32_32x32x16_bf16 v[80:95], v[240:243], v[248:251], v[80:95]
	global_load_lds_dwordx4 v131, s[46:47]
	s_add_u32 s70, s70, 0x40000
	s_addc_u32 s71, s71, 0
	s_add_u32 s72, s72, 0x2000
	s_addc_u32 s73, s73, 0
	s_waitcnt lgkmcnt(3)
	v_mfma_f32_32x32x16_bf16 v[64:79], v[244:247], v[248:251], v[64:79]
	ds_read_b128 v[240:243], v182
	ds_read_b128 v[244:247], v183
	ds_read_b128 v[248:251], v168
	s_waitcnt lgkmcnt(3)
	v_mfma_f32_32x32x16_bf16 v[80:95], v[224:227], v[232:235], v[80:95]
	s_waitcnt lgkmcnt(3)
	v_mfma_f32_32x32x16_bf16 v[64:79], v[228:231], v[232:235], v[64:79]
	ds_read_b128 v[224:227], v185
	ds_read_b128 v[228:231], v186
	ds_read_b128 v[232:235], v187
	s_waitcnt lgkmcnt(3)
	v_mfma_f32_32x32x16_bf16 v[80:95], v[240:243], v[248:251], v[80:95]
	s_waitcnt lgkmcnt(3)
	v_mfma_f32_32x32x16_bf16 v[64:79], v[244:247], v[248:251], v[64:79]
	ds_read_b64_tr_b16 v[240:241], v162 offset:0
	ds_read_b64_tr_b16 v[242:243], v162 offset:0x800
	ds_read_b64_tr_b16 v[244:245], v162 offset:0x1000
	ds_read_b64_tr_b16 v[246:247], v162 offset:0x1800
	ds_read_b64_tr_b16 v[248:249], v162 offset:0x2000
	ds_read_b64_tr_b16 v[250:251], v162 offset:0x2800
	ds_read_b64_tr_b16 v[148:149], v162 offset:0x3000
	ds_read_b64_tr_b16 v[150:151], v162 offset:0x3800
	s_waitcnt lgkmcnt(8)
	v_mfma_f32_32x32x16_bf16 v[80:95], v[224:227], v[232:235], v[80:95]
	v_add_f32_e32 v225, v207, v210
	v_mov_b32_e32 v226, v225
	s_nop 1
	v_permlane32_swap_b32_e32 v225, v226
	v_cvt_pk_bf16_f32 v210, v143, v144
	v_cvt_pk_bf16_f32 v144, v135, v137
	v_cvt_pk_bf16_f32 v137, v156, v157
	s_waitcnt lgkmcnt(8)
	v_mfma_f32_32x32x16_bf16 v[64:79], v[228:231], v[232:235], v[64:79]
	v_cvt_pk_bf16_f32 v143, v221, v207
	v_permlane32_swap_b32_e32 v210, v212
	v_permlane32_swap_b32_e32 v144, v146
	v_permlane32_swap_b32_e32 v137, v139
	v_permlane32_swap_b32_e32 v141, v143
	s_waitcnt lgkmcnt(0)
	s_nop 0
	v_mfma_f32_32x32x16_bf16 v[48:63], v[210:213], v[240:243], v[48:63]
	ds_read_b64_tr_b16 v[240:241], v162 offset:0x200
	ds_read_b64_tr_b16 v[242:243], v162 offset:0xa00
	v_max_f32_e32 v164, v81, v81
	v_max_f32_e32 v165, v80, v80
	v_max_f32_e32 v164, v165, v164
	v_max3_f32 v164, v164, v82, v83
	v_max3_f32 v164, v164, v84, v85
	v_mfma_f32_32x32x16_bf16 v[48:63], v[144:147], v[244:247], v[48:63]
	ds_read_b64_tr_b16 v[244:245], v162 offset:0x1200
	ds_read_b64_tr_b16 v[246:247], v162 offset:0x1a00
	v_max3_f32 v164, v164, v86, v87
	v_max3_f32 v164, v164, v88, v89
	v_max3_f32 v164, v164, v90, v91
	v_max3_f32 v164, v164, v92, v93
	v_max3_f32 v164, v164, v94, v95
	v_mfma_f32_32x32x16_bf16 v[48:63], v[136:139], v[248:251], v[48:63]
	ds_read_b64_tr_b16 v[248:249], v162 offset:0x2200
	ds_read_b64_tr_b16 v[250:251], v162 offset:0x2a00
	ds_read_b64_tr_b16 v[156:157], v162 offset:0x3200
	ds_read_b64_tr_b16 v[158:159], v162 offset:0x3a00
	v_max3_f32 v164, v164, v64, v65
	v_max3_f32 v164, v164, v66, v67
	v_max3_f32 v164, v164, v68, v69
	v_max3_f32 v164, v164, v70, v71
	v_max3_f32 v164, v164, v72, v73
	s_waitcnt lgkmcnt(0)
	v_mfma_f32_32x32x16_bf16 v[48:63], v[140:143], v[148:151], v[48:63]
	v_max3_f32 v164, v164, v74, v75
	v_max3_f32 v164, v164, v76, v77
	v_max3_f32 v164, v164, v78, v79
	v_mfma_f32_32x32x16_bf16 v[32:47], v[210:213], v[240:243], v[32:47]
	ds_read_b64_tr_b16 v[148:149], v162 offset:0x400
	ds_read_b64_tr_b16 v[150:151], v162 offset:0xc00
	ds_read_b64_tr_b16 v[240:241], v162 offset:0x1400
	ds_read_b64_tr_b16 v[242:243], v162 offset:0x1c00
	v_mov_b32_e32 v165, v164
	s_nop 1
	v_permlane32_swap_b32_e32 v164, v165
	v_max_f32_e32 v165, v165, v165
	v_max_f32_e32 v164, v164, v164
	v_max_f32_e32 v164, v164, v165
	v_mfma_f32_32x32x16_bf16 v[32:47], v[144:147], v[244:247], v[32:47]
	ds_read_b64_tr_b16 v[244:245], v162 offset:0x2400
	ds_read_b64_tr_b16 v[246:247], v162 offset:0x2c00
	v_max_f32_e32 v166, v134, v134
	v_sub_f32_e32 v165, v164, v134
	v_max_f32_e32 v164, v166, v164
	v_sub_f32_e32 v166, v134, v164
	v_mul_f32_e32 v166, 0x3dd53b94, v166
	v_mfma_f32_32x32x16_bf16 v[32:47], v[136:139], v[248:251], v[32:47]
	ds_read_b64_tr_b16 v[248:249], v162 offset:0x3400
	ds_read_b64_tr_b16 v[250:251], v162 offset:0x3c00
	v_exp_f32_e32 v166, v166
	v_cmp_ge_f32_e32 vcc, s69, v165
	s_cmp_eq_u64 vcc, exec
	s_cselect_b64 s[8:9], -1, 0
	v_cndmask_b32_e64 v207, v166, 1.0, s[8:9]
	v_cndmask_b32_e64 v195, v164, v134, s[8:9]
	v_mul_f32_e32 v168, 0xbdd53b94, v195
	v_mov_b32_e32 v187, v168
	s_waitcnt lgkmcnt(0)
; #define SBAR() __builtin_amdgcn_sched_barrier(0)
; __device__ __forceinline__ void partialSM(f32x16& p0, f32x16& p1, float& m_reg, float& mn, float& alpha) {
;   constexpr float C = ATT_SCALE * 1.4426950408889634f;
;   float pmax = p0[0];
; #pragma unroll
;   for (int r = 1; r < 16; ++r) pmax = fmaxf(pmax, p0[r]);
; #pragma unroll
;   for (int r = 0; r < 16; ++r) pmax = fmaxf(pmax, p1[r]);
;   { auto rr = __builtin_amdgcn_permlane32_swap(__float_as_uint(pmax), __float_as_uint(pmax), false, false);
;     pmax = fmaxf(__uint_as_float(rr[0]), __uint_as_float(rr[1])); }
;   if (__builtin_expect(__all(pmax - m_reg <= ATT_THR / ATT_SCALE), 1)) { mn = m_reg; alpha = 1.f; }
;   else { mn = fmaxf(m_reg, pmax); alpha = __builtin_amdgcn_exp2f((m_reg - mn) * C); m_reg = mn; }
;   const float mnC = -mn * C;
; #pragma unroll
;   for (int r = 0; r < 16; ++r) p0[r] = fmaf(p0[r], C, mnC);
; #pragma unroll
;   for (int r = 0; r < 16; ++r) p1[r] = fmaf(p1[r], C, mnC);
; #pragma unroll
;   for (int r = 0; r < 16; ++r) p0[r] = __builtin_amdgcn_exp2f(p0[r]);
; }
; template <int D0> __device__ __forceinline__ void pv_one(f32x16& od, int vb, bf16x8 pa0, bf16x8 pa1, bf16x8 pa2, bf16x8 pa3) {
;   const s16x4 l0 = tr_read<v_rd_off(D0, 0, 0)>(vb), h0 = tr_read<v_rd_off(D0, 0, 1)>(vb), l1 = tr_read<v_rd_off(D0, 1, 0)>(vb), h1 = tr_read<v_rd_off(D0, 1, 1)>(vb);
;   const s16x4 l2 = tr_read<v_rd_off(D0, 2, 0)>(vb), h2 = tr_read<v_rd_off(D0, 2, 1)>(vb), l3 = tr_read<v_rd_off(D0, 3, 0)>(vb), h3 = tr_read<v_rd_off(D0, 3, 1)>(vb);
;   asm volatile("s_waitcnt lgkmcnt(0)" ::: "memory"); SBAR();
;     ...
;   od = __builtin_amdgcn_mfma_f32_32x32x16_bf16(pa0, PK(l0, h0), od, 0, 0, 0);
;   od = __builtin_amdgcn_mfma_f32_32x32x16_bf16(pa1, PK(l1, h1), od, 0, 0, 0);
;   od = __builtin_amdgcn_mfma_f32_32x32x16_bf16(pa2, PK(l2, h2), od, 0, 0, 0);
;   od = __builtin_amdgcn_mfma_f32_32x32x16_bf16(pa3, PK(l3, h3), od, 0, 0, 0);
;     ...
; }
; __device__ __forceinline__ void pv_d0(f32x16* o, int vb, bf16x8 pa0, bf16x8 pa1, bf16x8 pa2, bf16x8 pa3) {
;   pv_one<0>(o[0], vb, pa0, pa1, pa2, pa3); pv_one<1>(o[1], vb, pa0, pa1, pa2, pa3); pv_one<2>(o[2], vb, pa0, pa1, pa2, pa3); pv_one<3>(o[3], vb, pa0, pa1, pa2, pa3);
; }
	v_mfma_f32_32x32x16_bf16 v[32:47], v[140:143], v[156:159], v[32:47]
	v_fmamk_f32 v80, v80, 0x3dd53b94, v168
	v_fmamk_f32 v81, v81, 0x3dd53b94, v168
	v_fmamk_f32 v82, v82, 0x3dd53b94, v168
	v_fmamk_f32 v83, v83, 0x3dd53b94, v168
	v_fmamk_f32 v84, v84, 0x3dd53b94, v168
	v_fmamk_f32 v85, v85, 0x3dd53b94, v168
	v_mfma_f32_32x32x16_bf16 v[16:31], v[210:213], v[148:151], v[16:31]
	ds_read_b64_tr_b16 v[148:149], v162 offset:0x600
	ds_read_b64_tr_b16 v[150:151], v162 offset:0xe00
	ds_read_b64_tr_b16 v[156:157], v162 offset:0x1600
	ds_read_b64_tr_b16 v[158:159], v162 offset:0x1e00
	v_fmamk_f32 v86, v86, 0x3dd53b94, v168
	v_fmamk_f32 v87, v87, 0x3dd53b94, v168
	v_fmamk_f32 v88, v88, 0x3dd53b94, v168
	v_fmamk_f32 v89, v89, 0x3dd53b94, v168
	v_fmamk_f32 v90, v90, 0x3dd53b94, v168
	v_fmamk_f32 v91, v91, 0x3dd53b94, v168
	v_mfma_f32_32x32x16_bf16 v[16:31], v[144:147], v[240:243], v[16:31]
	ds_read_b64_tr_b16 v[240:241], v162 offset:0x2600
	ds_read_b64_tr_b16 v[242:243], v162 offset:0x2e00
	v_fmamk_f32 v92, v92, 0x3dd53b94, v168
	v_fmamk_f32 v93, v93, 0x3dd53b94, v168
	v_fmamk_f32 v94, v94, 0x3dd53b94, v168
	v_fmac_f32_e32 v187, 0x3dd53b94, v95
	v_fmamk_f32 v134, v72, 0x3dd53b94, v168
	v_fmamk_f32 v135, v73, 0x3dd53b94, v168
	v_mfma_f32_32x32x16_bf16 v[16:31], v[136:139], v[244:247], v[16:31]
	ds_read_b64_tr_b16 v[244:245], v162 offset:0x3600
	ds_read_b64_tr_b16 v[246:247], v162 offset:0x3e00
	v_exp_f32_e32 v217, v81
	v_exp_f32_e32 v218, v82
	v_exp_f32_e32 v220, v83
	v_exp_f32_e32 v221, v84
	s_waitcnt lgkmcnt(0)
	v_mfma_f32_32x32x16_bf16 v[16:31], v[140:143], v[248:251], v[16:31]
	v_exp_f32_e32 v223, v85
	v_exp_f32_e32 v222, v86
	v_exp_f32_e32 v224, v87
	v_exp_f32_e32 v209, v88
	v_mfma_f32_32x32x16_bf16 v[0:15], v[210:213], v[148:151], v[0:15]
	v_fmamk_f32 v148, v74, 0x3dd53b94, v168
	v_fmamk_f32 v149, v75, 0x3dd53b94, v168
	v_exp_f32_e32 v214, v91
	v_exp_f32_e32 v215, v93
	v_exp_f32_e32 v216, v94
	v_mfma_f32_32x32x16_bf16 v[0:15], v[144:147], v[156:159], v[0:15]
	v_fmamk_f32 v146, v64, 0x3dd53b94, v168
	v_fmamk_f32 v147, v65, 0x3dd53b94, v168
	v_fmamk_f32 v144, v66, 0x3dd53b94, v168
	v_fmamk_f32 v145, v67, 0x3dd53b94, v168
	v_exp_f32_e32 v219, v187
	v_exp_f32_e32 v213, v80
	v_mfma_f32_32x32x16_bf16 v[0:15], v[136:139], v[240:243], v[0:15]
	v_fmamk_f32 v136, v70, 0x3dd53b94, v168
	v_fmamk_f32 v137, v71, 0x3dd53b94, v168
	v_fmamk_f32 v138, v78, 0x3dd53b94, v168
	v_fmamk_f32 v139, v79, 0x3dd53b94, v168
	v_exp_f32_e32 v210, v89
	v_exp_f32_e32 v211, v90
	v_mfma_f32_32x32x16_bf16 v[0:15], v[140:143], v[244:247], v[0:15]
	v_fmamk_f32 v140, v68, 0x3dd53b94, v168
	v_fmamk_f32 v141, v69, 0x3dd53b94, v168
	v_fmamk_f32 v142, v76, 0x3dd53b94, v168
	v_fmamk_f32 v143, v77, 0x3dd53b94, v168
	v_exp_f32_e32 v212, v92
	v_cmp_gt_f32_e32 vcc, 1.0, v207
	s_cbranch_vccz .LBB0_361
	s_and_saveexec_b64 s[10:11], s[6:7]
	ds_write_b32 v160, v207 offset:128
	s_or_b64 exec, exec, s[10:11]
	s_waitcnt lgkmcnt(0)
	v_add_u32_e32 v150, v253, v128
	ds_read_b128 v[240:243], v150 offset:224
	ds_read_b128 v[244:247], v150 offset:192
	ds_read_b128 v[248:251], v150 offset:160
	ds_read_b128 v[156:159], v150 offset:128
	s_waitcnt lgkmcnt(3)
	v_pk_mul_f32 v[60:61], v[60:61], v[240:241]
	s_waitcnt lgkmcnt(2)
	v_pk_mul_f32 v[56:57], v[56:57], v[244:245]
	s_waitcnt lgkmcnt(1)
	v_pk_mul_f32 v[52:53], v[52:53], v[248:249]
	v_pk_mul_f32 v[62:63], v[62:63], v[242:243]
	v_pk_mul_f32 v[58:59], v[58:59], v[246:247]
	v_pk_mul_f32 v[54:55], v[54:55], v[250:251]
	s_waitcnt lgkmcnt(0)
	v_pk_mul_f32 v[50:51], v[50:51], v[158:159]
	v_pk_mul_f32 v[48:49], v[48:49], v[156:157]
	v_pk_mul_f32 v[44:45], v[44:45], v[240:241]
	v_pk_mul_f32 v[40:41], v[40:41], v[244:245]
	v_pk_mul_f32 v[36:37], v[36:37], v[248:249]
	v_pk_mul_f32 v[46:47], v[46:47], v[242:243]
	v_pk_mul_f32 v[42:43], v[42:43], v[246:247]
	v_pk_mul_f32 v[38:39], v[38:39], v[250:251]
	v_pk_mul_f32 v[34:35], v[34:35], v[158:159]
	v_pk_mul_f32 v[32:33], v[32:33], v[156:157]
	v_pk_mul_f32 v[28:29], v[28:29], v[240:241]
	v_pk_mul_f32 v[24:25], v[24:25], v[244:245]
	v_pk_mul_f32 v[20:21], v[20:21], v[248:249]
	v_pk_mul_f32 v[30:31], v[30:31], v[242:243]
	v_pk_mul_f32 v[26:27], v[26:27], v[246:247]
	v_pk_mul_f32 v[22:23], v[22:23], v[250:251]
	v_pk_mul_f32 v[18:19], v[18:19], v[158:159]
	v_pk_mul_f32 v[16:17], v[16:17], v[156:157]
	v_pk_mul_f32 v[12:13], v[12:13], v[240:241]
	v_pk_mul_f32 v[8:9], v[8:9], v[244:245]
	v_pk_mul_f32 v[4:5], v[4:5], v[248:249]
	v_pk_mul_f32 v[14:15], v[14:15], v[242:243]
	v_pk_mul_f32 v[10:11], v[10:11], v[246:247]
	v_pk_mul_f32 v[6:7], v[6:7], v[250:251]
	v_pk_mul_f32 v[2:3], v[2:3], v[158:159]
	v_pk_mul_f32 v[0:1], v[0:1], v[156:157]
